# P4->P5 seam split for the late group: arrive at the grid barrier before the w_down conversion, run the conversion while the other workgroups arrive, wait afterwards
# baseline (speedup 1.0000x reference)
.LBB0_613:
	s_andn2_b64 vcc, exec, s[6:7]
	s_cbranch_vccnz .LBB0_618
	s_cmpk_gt_i32 s17, 0x7f
	s_cbranch_scc1 .LBB0_618
	s_waitcnt vmcnt(0)
	s_barrier
	s_mov_b64 s[4:5], exec
	v_readlane_b32 s0, v255, 1
	v_readlane_b32 s1, v255, 2
	s_and_b64 s[0:1], s[4:5], s[0:1]
	s_mov_b64 exec, s[0:1]
	s_cbranch_execz .Lgb4s_others
	s_getreg_b32 s0, hwreg(HW_REG_XCC_ID, 0, 4)
	v_mov_b32_e32 v0, 0x23fc0
	ds_read_b64 v[2:3], v0
	s_and_b32 s0, s0, 15
	s_lshl_b32 s1, s0, 8
	s_add_u32 s6, s54, s1
	s_addc_u32 s7, s55, 0
	v_mov_b32_e32 v0, 0x1000
	v_mov_b32_e32 v1, 1
	global_atomic_add v1, v0, v1, s[6:7] offset:1024 sc0
	s_waitcnt lgkmcnt(0)
	v_readfirstlane_b32 s8, v2
	v_readfirstlane_b32 s9, v3
	s_mul_i32 s8, s8, 3
	s_mul_i32 s9, s9, 3
	v_mov_b32_e32 v0, 0x3000
	s_waitcnt vmcnt(0)
	v_readfirstlane_b32 s0, v1
	s_add_u32 s0, s0, 1
	s_cmp_lg_u32 s0, s8
	s_cbranch_scc0 .Lgb4s_lead
	s_branch .Lgb4s_arrived
.Lgb4s_lead:
	buffer_wbl2 sc1
	s_waitcnt vmcnt(0)
	v_mov_b32_e32 v1, 1
	global_atomic_add v0, v1, s[54:55] offset:1024
	s_branch .Lgb4s_arrived

.Lgb4s_arrived:
	s_or_b64 exec, exec, s[4:5]
	v_and_b32_e32 v110, 63, v252
	v_lshrrev_b32_e32 v0, 6, v252
	v_writelane_b32 v111, s16, 0
	v_writelane_b32 v111, s17, 1
	v_writelane_b32 v111, s18, 2
	v_writelane_b32 v111, s19, 3
	v_writelane_b32 v111, s20, 4
	v_writelane_b32 v111, s21, 5
	v_writelane_b32 v111, s22, 6
	v_writelane_b32 v111, s23, 7
	v_writelane_b32 v111, s24, 8
	v_writelane_b32 v111, s25, 9
	v_writelane_b32 v111, s26, 10
	v_writelane_b32 v111, s27, 11
	v_readfirstlane_b32 s0, v0
	s_mul_i32 s1, s0, 0x4100
	s_lshl_b32 s16, s17, 3
	s_add_u32 s16, s16, s0
	s_add_u32 s16, s16, 0x300
	s_cmp_lt_u32 s16, 0xb00
	s_cbranch_scc0 .Lcv_wdl_skip
	v_lshrrev_b32_e32 v0, 4, v110
	v_and_b32_e32 v1, 15, v110
	v_and_b32_e32 v2, 7, v110
	v_lshrrev_b32_e32 v3, 3, v110
	v_mul_u32_u24_e32 v64, 0x2000, v0
	v_lshl_add_u32 v64, v1, 4, v64
	v_mul_u32_u24_e32 v65, 0x104, v0
	v_lshl_add_u32 v65, v1, 4, v65
	v_add_u32_e32 v65, s1, v65
	v_mul_u32_u24_e32 v66, 0x820, v2
	v_lshl_add_u32 v66, v3, 2, v66
	v_add_u32_e32 v66, s1, v66
	v_add_u32_e32 v67, 0x410, v66
	v_mul_u32_u24_e32 v68, 0x2c00, v3
	v_lshl_add_u32 v68, v2, 4, v68
	v_mov_b32_e32 v4, 0x23fa0
	ds_read_b64 v[0:1], v4
	s_waitcnt lgkmcnt(0)
	v_readfirstlane_b32 s18, v0
	v_readfirstlane_b32 s19, v1
	s_add_u32 s26, s54, 0x4800000
	s_addc_u32 s27, s55, 0
	s_nop 4
	s_lshr_b32 s98, s16, 5
	s_and_b32 s99, s16, 31
	s_lshl_b32 s0, s98, 19
	s_lshl_b32 s100, s99, 8
	s_add_u32 s0, s0, s100
	s_add_u32 s4, s18, s0
	s_addc_u32 s5, s19, 0
	s_mul_i32 s0, s99, 0xb0000
	s_lshl_b32 s100, s98, 7
	s_add_u32 s0, s0, s100
	s_add_u32 s24, s26, s0
	s_addc_u32 s25, s27, 0
	global_load_dwordx4 v[0:3], v64, s[4:5] nt
	s_add_u32 s4, s4, 0x8000
	s_addc_u32 s5, s5, 0
	global_load_dwordx4 v[4:7], v64, s[4:5] nt
	s_add_u32 s4, s4, 0x8000
	s_addc_u32 s5, s5, 0
	global_load_dwordx4 v[8:11], v64, s[4:5] nt
	s_add_u32 s4, s4, 0x8000
	s_addc_u32 s5, s5, 0
	global_load_dwordx4 v[12:15], v64, s[4:5] nt
	s_add_u32 s4, s4, 0x8000
	s_addc_u32 s5, s5, 0
	global_load_dwordx4 v[16:19], v64, s[4:5] nt
	s_add_u32 s4, s4, 0x8000
	s_addc_u32 s5, s5, 0
	global_load_dwordx4 v[20:23], v64, s[4:5] nt
	s_add_u32 s4, s4, 0x8000
	s_addc_u32 s5, s5, 0
	global_load_dwordx4 v[24:27], v64, s[4:5] nt
	s_add_u32 s4, s4, 0x8000
	s_addc_u32 s5, s5, 0
	global_load_dwordx4 v[28:31], v64, s[4:5] nt
	s_add_u32 s4, s4, 0x8000
	s_addc_u32 s5, s5, 0
	global_load_dwordx4 v[32:35], v64, s[4:5] nt
	s_add_u32 s4, s4, 0x8000
	s_addc_u32 s5, s5, 0
	global_load_dwordx4 v[36:39], v64, s[4:5] nt
	s_add_u32 s4, s4, 0x8000
	s_addc_u32 s5, s5, 0
	global_load_dwordx4 v[40:43], v64, s[4:5] nt
	s_add_u32 s4, s4, 0x8000
	s_addc_u32 s5, s5, 0
	global_load_dwordx4 v[44:47], v64, s[4:5] nt
	s_add_u32 s4, s4, 0x8000
	s_addc_u32 s5, s5, 0
	global_load_dwordx4 v[48:51], v64, s[4:5] nt
	s_add_u32 s4, s4, 0x8000
	s_addc_u32 s5, s5, 0
	global_load_dwordx4 v[52:55], v64, s[4:5] nt
	s_add_u32 s4, s4, 0x8000
	s_addc_u32 s5, s5, 0
	global_load_dwordx4 v[56:59], v64, s[4:5] nt
	s_add_u32 s4, s4, 0x8000
	s_addc_u32 s5, s5, 0
	global_load_dwordx4 v[60:63], v64, s[4:5] nt
	s_waitcnt vmcnt(0)
	s_branch .Lcv_wdl_body

.Lgb4s_wait:
	s_waitcnt vmcnt(0)
	s_mov_b64 s[4:5], exec
	v_readlane_b32 s0, v255, 1
	v_readlane_b32 s1, v255, 2
	s_and_b64 s[0:1], s[4:5], s[0:1]
	s_mov_b64 exec, s[0:1]
	s_cbranch_execz .LBB0_670
	v_mov_b32_e32 v0, 0x23fc4
	ds_read_b32 v1, v0
	s_waitcnt lgkmcnt(0)
	v_readfirstlane_b32 s9, v1
	s_mul_i32 s9, s9, 3
	v_mov_b32_e32 v0, 0x3000
	s_mov_b32 s1, 0
.Lgb4s_spin:
	global_load_dword v1, v0, s[54:55] offset:1024 sc1
	s_waitcnt vmcnt(0)
	v_readfirstlane_b32 s0, v1
	s_cmp_ge_u32 s0, s9
	s_cbranch_scc1 .LBB0_670
	s_sleep 1
	s_add_u32 s1, s1, 1
	s_cmp_lt_u32 s1, 0x40000
	s_cbranch_scc1 .Lgb4s_spin
	s_branch .LBB0_670
.LBB0_618:
	s_waitcnt vmcnt(0)
	s_barrier
	s_mov_b64 s[4:5], exec
	v_readlane_b32 s0, v255, 1
	v_readlane_b32 s1, v255, 2
	s_and_b64 s[0:1], s[4:5], s[0:1]
	s_mov_b64 exec, s[0:1]
	s_cbranch_execz .Lgb4_others
	s_getreg_b32 s0, hwreg(HW_REG_XCC_ID, 0, 4)
	v_mov_b32_e32 v0, 0x23fc0
	ds_read_b64 v[2:3], v0
	s_and_b32 s0, s0, 15
	s_lshl_b32 s1, s0, 8
	s_add_u32 s6, s54, s1
	s_addc_u32 s7, s55, 0
	v_mov_b32_e32 v0, 0x1000
	v_mov_b32_e32 v1, 1
	global_atomic_add v1, v0, v1, s[6:7] offset:1024 sc0
	s_waitcnt lgkmcnt(0)
	v_readfirstlane_b32 s8, v2
	v_readfirstlane_b32 s9, v3
	s_mul_i32 s8, s8, 3
	s_mul_i32 s9, s9, 3
	v_mov_b32_e32 v0, 0x3000
	s_waitcnt vmcnt(0)
	v_readfirstlane_b32 s0, v1
	s_add_u32 s0, s0, 1
	s_cmp_lg_u32 s0, s8
	s_cbranch_scc0 .Lgb4_lead
	s_branch .Lgb4_wait
